# S5-Y: scalar-base DMA addressing in the k-loop (SGPR base + constant lane offset) plus vblock-local LDS-counter barrier
# baseline (speedup 1.0000x reference)
; #define MFMA16(a, b, c) __builtin_amdgcn_mfma_f32_16x16x32_bf16((a), (b), (c), 0, 0, 0)
; template <class FA, class FB, class FL, class FS>
; DI void gemm_tile(char* lds, int ksteps, int rot, FA fa, FB fb, FL fl, FS fs) {
;     ...
;     const char* A = lds + cur * 32768;
;     const char* B = A + 16384;
; #pragma unroll
;     for (int kk = 0; kk < 2; ++kk) {
;       bf16x8 af[4], bq[4];
; #pragma unroll
;       for (int m = 0; m < 4; ++m) af[m] = ldfrag(A, 128, wr * 64 + m * 16 + fr, kk * 4 + fq);
; #pragma unroll
;       for (int n = 0; n < 4; ++n) bq[n] = ldfrag(B, 128, wc * 64 + n * 16 + fr, kk * 4 + fq);
; #pragma unroll
;       for (int m = 0; m < 4; ++m)
; #pragma unroll
;         for (int n = 0; n < 4; ++n) acc[m][n] = MFMA16(bq[n], af[m], acc[m][n]);
;     }
;     asm volatile("s_waitcnt vmcnt(0)" ::: "memory");
;     __syncthreads();
; DI void phase_s5_y(const Params& p, char* lds) {
;     ...
;       [&](int r, int kc) { return kc < 16 ? Hg + (size_t)r * 128 + kc * 8 : Ug + (size_t)r * 512 + (kc - 16) * 8; },
;       [&](int n, int kc) {
;         const int nn = j * 128 + n;
;         if (kc < 16) return MC + ((size_t)g * 512 + nn) * 128 + kc * 8;
;         const int t = nn >> 4, co = nn & 15, kk = (kc - 16) * 8, s = kk >> 4, ci0 = kk & 15;
;         if (s > t) return zblk;
;         return KT + ((size_t)(g * 16 + co) * 32 + (t - s)) * 16 + ci0;
.Ls5sb_done1:
	s_mov_b64 exec, s[68:69]
	s_nop 1
	v_mfma_f32_16x16x32_bf16 v[64:67], v[124:127], v[18:21], v[36:39]
	v_mfma_f32_16x16x32_bf16 v[60:63], v[132:135], v[18:21], v[44:47]
	v_mfma_f32_16x16x32_bf16 v[56:59], v[140:143], v[18:21], v[48:51]
	v_mfma_f32_16x16x32_bf16 v[48:51], v[124:127], v[32:35], v[72:75]
	v_mfma_f32_16x16x32_bf16 v[44:47], v[132:135], v[32:35], v[92:95]
	s_nop 1
	v_lshlrev_b32_e32 v72, 10, v155
	v_mov_b32_e32 v73, v69
	v_lshlrev_b32_e32 v74, 10, v156
	v_mfma_f32_16x16x32_bf16 v[40:43], v[140:143], v[32:35], v[96:99]
	v_lshrrev_b32_e32 v92, 4, v0
	v_lshrrev_b32_e32 v93, 4, v2
	v_lshrrev_b32_e32 v94, 4, v4
	v_mfma_f32_16x16x32_bf16 v[36:39], v[144:147], v[32:35], v[28:31]
	v_lshrrev_b32_e32 v95, 4, v6
	v_mov_b32_e32 v75, v69
	v_lshl_add_u64 v[72:73], v[152:153], 0, v[72:73]
	v_mfma_f32_16x16x32_bf16 v[32:35], v[124:127], v[12:15], v[104:107]
	v_lshl_add_u64 v[74:75], v[152:153], 0, v[74:75]
	v_lshlrev_b32_e32 v96, 3, v158
	v_lshlrev_b32_e32 v97, 3, v159
	v_mfma_f32_16x16x32_bf16 v[28:31], v[132:135], v[12:15], v[108:111]
	v_lshlrev_b32_e32 v98, 3, v160
	v_lshlrev_b32_e32 v99, 3, v161
	v_mfma_f32_16x16x32_bf16 v[20:23], v[140:143], v[12:15], v[112:115]
	v_mfma_f32_16x16x32_bf16 v[16:19], v[144:147], v[12:15], v[116:119]
	v_mfma_f32_16x16x32_bf16 v[12:15], v[124:127], v[148:151], v[8:11]
	v_mfma_f32_16x16x32_bf16 v[8:11], v[132:135], v[148:151], v[120:123]
	v_mfma_f32_16x16x32_bf16 v[4:7], v[140:143], v[148:151], v[128:131]
	v_mfma_f32_16x16x32_bf16 v[0:3], v[144:147], v[148:151], v[136:139]
	v_readfirstlane_b32 s45, v91
	v_readfirstlane_b32 s52, v152
	v_readfirstlane_b32 s53, v153
	v_bfe_u32 v163, v182, 3, 5
	v_lshlrev_b32_e32 v162, 1, v96
	v_lshl_or_b32 v163, v163, 10, v162
	v_lshrrev_b32_e32 v162, 4, v96
	v_sub_u32_e32 v164, v92, v162
	v_and_b32_e32 v162, 8, v96
	v_lshlrev_b32_e32 v162, 1, v162
	v_lshl_add_u32 v165, v164, 5, v162
	v_subrev_u32_e32 v162, s30, v26
	v_add_u32_e32 v165, v165, v162
	v_and_b32_e32 v162, 0xff, v182
	v_lshl_add_u32 v162, v162, 4, v102
	s_nop 1
	v_readfirstlane_b32 s48, v162
	s_branch .LBB0_627
.LBB0_626:
	v_add_u32_e32 v68, s40, v102
	v_add_u32_e32 v101, v68, v87
	v_add_u32_e32 v124, v101, v88
	ds_read_b128 v[104:107], v124 offset:16384
	v_add_u32_e32 v101, v101, v89
	ds_read_b128 v[108:111], v124 offset:18432
	ds_read_b128 v[112:115], v101
	ds_read_b128 v[116:119], v101 offset:2048
	ds_read_b128 v[120:123], v124 offset:20480
	ds_read_b128 v[124:127], v124 offset:22528
	s_waitcnt lgkmcnt(0)
	v_mfma_f32_16x16x32_bf16 v[60:63], v[108:111], v[112:115], v[60:63]
	v_add_u32_e32 v68, v68, v90
	s_add_i32 s37, s37, 1
	s_add_i32 s39, s39, 0x8000
	v_mfma_f32_16x16x32_bf16 v[64:67], v[104:107], v[112:115], v[64:67]
	s_add_i32 s38, s38, 64
	v_cmp_eq_u32_e32 vcc, s37, v100
	s_or_b64 s[0:1], vcc, s[0:1]
	v_mfma_f32_16x16x32_bf16 v[56:59], v[120:123], v[112:115], v[56:59]
	v_mfma_f32_16x16x32_bf16 v[52:55], v[124:127], v[112:115], v[52:55]
	v_mfma_f32_16x16x32_bf16 v[48:51], v[104:107], v[116:119], v[48:51]
	v_mfma_f32_16x16x32_bf16 v[44:47], v[108:111], v[116:119], v[44:47]
	v_mfma_f32_16x16x32_bf16 v[40:43], v[120:123], v[116:119], v[40:43]
	v_mfma_f32_16x16x32_bf16 v[36:39], v[124:127], v[116:119], v[36:39]
	ds_read_b128 v[112:115], v101 offset:4096
	ds_read_b128 v[116:119], v101 offset:6144
	v_add_u32_e32 v101, v68, v88
	v_add_u32_e32 v68, v68, v89
	s_waitcnt lgkmcnt(1)
	v_mfma_f32_16x16x32_bf16 v[32:35], v[104:107], v[112:115], v[32:35]
	v_mfma_f32_16x16x32_bf16 v[28:31], v[108:111], v[112:115], v[28:31]
	v_mfma_f32_16x16x32_bf16 v[20:23], v[120:123], v[112:115], v[20:23]
	v_mfma_f32_16x16x32_bf16 v[16:19], v[124:127], v[112:115], v[16:19]
	s_waitcnt lgkmcnt(0)
	v_mfma_f32_16x16x32_bf16 v[12:15], v[104:107], v[116:119], v[12:15]
	ds_read_b128 v[104:107], v101 offset:16384
	v_mfma_f32_16x16x32_bf16 v[8:11], v[108:111], v[116:119], v[8:11]
	v_mfma_f32_16x16x32_bf16 v[4:7], v[120:123], v[116:119], v[4:7]
	v_mfma_f32_16x16x32_bf16 v[0:3], v[124:127], v[116:119], v[0:3]
	ds_read_b128 v[108:111], v101 offset:18432
	ds_read_b128 v[112:115], v68
	ds_read_b128 v[116:119], v68 offset:2048
	ds_read_b128 v[120:123], v101 offset:20480
	ds_read_b128 v[124:127], v101 offset:22528
	s_waitcnt lgkmcnt(3)
	v_mfma_f32_16x16x32_bf16 v[64:67], v[104:107], v[112:115], v[64:67]
	v_mfma_f32_16x16x32_bf16 v[60:63], v[108:111], v[112:115], v[60:63]
	s_waitcnt lgkmcnt(1)
	v_mfma_f32_16x16x32_bf16 v[56:59], v[120:123], v[112:115], v[56:59]
	s_waitcnt lgkmcnt(0)
	v_mfma_f32_16x16x32_bf16 v[52:55], v[124:127], v[112:115], v[52:55]
	v_mfma_f32_16x16x32_bf16 v[48:51], v[104:107], v[116:119], v[48:51]
	v_mfma_f32_16x16x32_bf16 v[44:47], v[108:111], v[116:119], v[44:47]
	v_mfma_f32_16x16x32_bf16 v[40:43], v[120:123], v[116:119], v[40:43]
	v_mfma_f32_16x16x32_bf16 v[36:39], v[124:127], v[116:119], v[36:39]
	ds_read_b128 v[112:115], v68 offset:4096
	ds_read_b128 v[116:119], v68 offset:6144
	s_waitcnt vmcnt(0)
	s_waitcnt lgkmcnt(0)
	v_mfma_f32_16x16x32_bf16 v[32:35], v[104:107], v[112:115], v[32:35]
	s_add_i32 s66, s66, 4
	s_mov_b64 s[68:69], exec
	s_mov_b64 exec, 1
	s_nop 1
	ds_add_u32 v168, v169
	s_movk_i32 s67, 0x800

; #define LAS __attribute__((address_space(3)))
; template <class FA, class FB, class FL, class FS>
; DI void gemm_tile(char* lds, int ksteps, int rot, FA fa, FB fb, FL fl, FS fs) {
;     ...
;     if (ks + 1 < ksteps) {
;       int kn = ks + 1 + rot; if (kn >= ksteps) kn -= ksteps;
;       LAS char* dst = l3 + (cur ^ 1) * 32768;
; #pragma unroll
;       for (int i = 0; i < 4; ++i) {
;         const int id = tid + i * 256, r = id >> 3, c = (id & 7) ^ (r & 7);
;         __builtin_amdgcn_global_load_lds((const unsigned*)fa(r, kn * 8 + c), (LAS unsigned*)(dst + id * 16), 16, 0, 0);
;         __builtin_amdgcn_global_load_lds((const unsigned*)fb(r, kn * 8 + c), (LAS unsigned*)(dst + 16384 + id * 16), 16, 0, 0);
;       }
;     }
; DI void phase_s5_y(const Params& p, char* lds) {
;     ...
;       [&](int r, int kc) { return kc < 16 ? Hg + (size_t)r * 128 + kc * 8 : Ug + (size_t)r * 512 + (kc - 16) * 8; },
;       [&](int n, int kc) {
;         const int nn = j * 128 + n;
;         if (kc < 16) return MC + ((size_t)g * 512 + nn) * 128 + kc * 8;
;         const int t = nn >> 4, co = nn & 15, kk = (kc - 16) * 8, s = kk >> 4, ci0 = kk & 15;
;         if (s > t) return zblk;
;         return KT + ((size_t)(g * 16 + co) * 32 + (t - s)) * 16 + ci0;
.LBB0_627:
	s_and_b32 s40, s39, 0x8000
	s_add_i32 s2, s37, 11
	s_cmp_ge_u32 s2, s45
	s_cbranch_scc1 .LBB0_626
	s_xor_b32 s41, s40, 0x8000
	s_lshl_b32 s54, s38, 1
	s_add_u32 s56, s52, s54
	s_addc_u32 s57, s53, 0
	s_add_i32 s58, s41, s48
	s_lshr_b32 s59, s38, 4
	s_add_i32 m0, s58, 0x0
	s_nop 0
	global_load_lds_dwordx4 v163, s[56:57]
	s_add_u32 s56, s56, 0x8000
	s_addc_u32 s57, s57, 0
	s_add_i32 m0, s58, 0x1000
	s_nop 0
	global_load_lds_dwordx4 v163, s[56:57]
	s_add_u32 s56, s56, 0x8000
	s_addc_u32 s57, s57, 0
	s_add_i32 m0, s58, 0x2000
	s_nop 0
	global_load_lds_dwordx4 v163, s[56:57]
	s_add_u32 s56, s56, 0x8000
	s_addc_u32 s57, s57, 0
	s_add_i32 m0, s58, 0x3000
	s_nop 0
	global_load_lds_dwordx4 v163, s[56:57]
	v_cmp_le_i32_e32 vcc, s59, v164
	v_subrev_u32_e32 v104, s54, v165
	s_add_i32 m0, s58, 0x4000
	v_cndmask_b32_e32 v104, 0, v104, vcc
	global_load_lds_dwordx4 v104, s[30:31]
	s_sub_i32 s59, s59, 2
	s_sub_i32 s54, s54, 64
	v_cmp_le_i32_e32 vcc, s59, v164
	v_subrev_u32_e32 v104, s54, v165
	s_add_i32 m0, s58, 0x5000
	v_cndmask_b32_e32 v104, 0, v104, vcc
	global_load_lds_dwordx4 v104, s[30:31]
	s_sub_i32 s59, s59, 2
	s_sub_i32 s54, s54, 64
	v_cmp_le_i32_e32 vcc, s59, v164
	v_subrev_u32_e32 v104, s54, v165
	s_add_i32 m0, s58, 0x6000
	v_cndmask_b32_e32 v104, 0, v104, vcc
	global_load_lds_dwordx4 v104, s[30:31]
	s_sub_i32 s59, s59, 2
	s_sub_i32 s54, s54, 64
	v_cmp_le_i32_e32 vcc, s59, v164
	v_subrev_u32_e32 v104, s54, v165
	s_add_i32 m0, s58, 0x7000
	v_cndmask_b32_e32 v104, 0, v104, vcc
	global_load_lds_dwordx4 v104, s[30:31]
	s_branch .LBB0_626
